# all s_setprio removed (generic GEMM loop and attention too)
# baseline (speedup 1.0000x reference)
.LBB0_106:
	s_lshl_b64 s[14:15], s[4:5], 17
	s_lshl_b32 s4, s37, 13
	v_lshl_add_u64 v[48:49], v[146:147], 0, s[14:15]
	s_add_i32 s4, s33, s4
	v_lshl_add_u64 v[48:49], v[48:49], 0, s[20:21]
	s_add_i32 m0, s4, 0x9000
	s_mul_i32 s4, s43, 0x3000
	global_load_lds_dwordx4 v[48:49], off
	s_add_i32 s4, s4, 16
	v_add_u32_e32 v52, s4, v149
	ds_read_b128 v[48:51], v52
	ds_read_b128 v[106:109], v52 offset:32
	ds_read_b128 v[64:67], v52 offset:6144
	ds_read_b128 v[110:113], v52 offset:6176
	ds_read_b128 v[114:117], v52 offset:64
	ds_read_b128 v[118:121], v52 offset:96
	ds_read_b128 v[122:125], v52 offset:6208
	ds_read_b128 v[126:129], v52 offset:6240
	v_add_u32_e32 v52, s4, v150
	ds_read_b128 v[132:135], v52
	ds_read_b128 v[160:163], v52 offset:6144
	v_add_u32_e32 v52, s4, v151
	ds_read_b128 v[164:167], v52
	ds_read_b128 v[168:171], v52 offset:6144
	s_waitcnt lgkmcnt(0)
	v_mfma_f32_32x32x16_bf16 v[48:63], v[48:51], v[82:85], 0
	v_mfma_f32_32x32x16_bf16 v[64:79], v[64:67], v[82:85], 0
	v_mfma_f32_32x32x16_bf16 v[48:63], v[106:109], v[86:89], v[48:63]
	v_mfma_f32_32x32x16_bf16 v[64:79], v[110:113], v[86:89], v[64:79]
	v_mfma_f32_32x32x16_bf16 v[48:63], v[114:117], v[90:93], v[48:63]
	v_mfma_f32_32x32x16_bf16 v[64:79], v[122:125], v[90:93], v[64:79]
	v_mfma_f32_32x32x16_bf16 v[48:63], v[118:121], v[94:97], v[48:63]
	v_mfma_f32_32x32x16_bf16 v[64:79], v[126:129], v[94:97], v[64:79]
	v_mfma_f32_32x32x16_bf16 v[48:63], v[132:135], v[98:101], v[48:63]
	v_mfma_f32_32x32x16_bf16 v[64:79], v[160:163], v[98:101], v[64:79]
	v_mfma_f32_32x32x16_bf16 v[48:63], v[164:167], v[102:105], v[48:63]
	v_mfma_f32_32x32x16_bf16 v[64:79], v[168:171], v[102:105], v[64:79]
	v_lshl_add_u32 v108, s43, 13, v131
	ds_read_b64_tr_b16 v[132:133], v108 offset:0
	ds_read_b64_tr_b16 v[134:135], v108 offset:1024
	ds_read_b64_tr_b16 v[160:161], v108 offset:64
	ds_read_b64_tr_b16 v[162:163], v108 offset:1088
	ds_read_b64_tr_b16 v[126:127], v108 offset:2048
	ds_read_b64_tr_b16 v[128:129], v108 offset:3072
	ds_read_b64_tr_b16 v[122:123], v108 offset:2112
	ds_read_b64_tr_b16 v[124:125], v108 offset:3136
	ds_read_b64_tr_b16 v[118:119], v108 offset:4096
	ds_read_b64_tr_b16 v[120:121], v108 offset:5120
	ds_read_b64_tr_b16 v[114:115], v108 offset:4160
	ds_read_b64_tr_b16 v[116:117], v108 offset:5184
	ds_read_b64_tr_b16 v[110:111], v108 offset:6144
	ds_read_b64_tr_b16 v[112:113], v108 offset:7168
	ds_read_b64_tr_b16 v[106:107], v108 offset:6208
	ds_read_b64_tr_b16 v[108:109], v108 offset:7232
	s_nop 8
	v_exp_f32_e32 v50, v50
	v_exp_f32_e32 v51, v51
	v_exp_f32_e32 v52, v52
	v_exp_f32_e32 v53, v53
	v_exp_f32_e32 v54, v54
	v_exp_f32_e32 v55, v55
	v_exp_f32_e32 v48, v48
	v_exp_f32_e32 v49, v49
	v_add_f32_e32 v32, v32, v50
	v_add_f32_e32 v33, v33, v51
	v_add_f32_e32 v34, v34, v52
	v_add_f32_e32 v35, v35, v53
	v_add_f32_e32 v32, v32, v54
	v_add_f32_e32 v33, v33, v55
	v_add_f32_e32 v34, v34, v48
	v_add_f32_e32 v35, v35, v49
	s_waitcnt lgkmcnt(0)
	v_cvt_pk_bf16_f32 v48, v48, v49
	v_cvt_pk_bf16_f32 v49, v50, v51
	v_cvt_pk_bf16_f32 v50, v52, v53
	v_cvt_pk_bf16_f32 v51, v54, v55
	s_nop 1
	v_mfma_f32_32x32x16_bf16 v[0:15], v[132:135], v[48:51], v[0:15]
	v_exp_f32_e32 v56, v56
	v_exp_f32_e32 v57, v57
	v_exp_f32_e32 v58, v58
	v_exp_f32_e32 v59, v59
	v_exp_f32_e32 v60, v60
	v_exp_f32_e32 v61, v61
	v_exp_f32_e32 v62, v62
	v_mfma_f32_32x32x16_bf16 v[16:31], v[160:163], v[48:51], v[16:31]
	v_exp_f32_e32 v63, v63
	v_exp_f32_e32 v64, v64
	v_exp_f32_e32 v65, v65
	v_exp_f32_e32 v66, v66
	v_exp_f32_e32 v67, v67
	v_exp_f32_e32 v68, v68
	v_exp_f32_e32 v69, v69
	v_add_f32_e32 v32, v32, v56
	v_add_f32_e32 v33, v33, v57
	v_add_f32_e32 v34, v34, v58
	v_add_f32_e32 v35, v35, v59
	v_add_f32_e32 v32, v32, v60
	v_add_f32_e32 v33, v33, v61
	v_add_f32_e32 v34, v34, v62
	v_add_f32_e32 v35, v35, v63
	v_cvt_pk_bf16_f32 v48, v56, v57
	v_cvt_pk_bf16_f32 v49, v58, v59
	v_cvt_pk_bf16_f32 v50, v60, v61
	v_cvt_pk_bf16_f32 v51, v62, v63
	v_exp_f32_e32 v70, v70
	v_exp_f32_e32 v71, v71
	v_exp_f32_e32 v72, v72
	v_mfma_f32_32x32x16_bf16 v[0:15], v[126:129], v[48:51], v[0:15]
	v_exp_f32_e32 v73, v73
	v_exp_f32_e32 v74, v74
	v_exp_f32_e32 v75, v75
	v_exp_f32_e32 v76, v76
	v_exp_f32_e32 v77, v77
	v_exp_f32_e32 v78, v78
	v_exp_f32_e32 v79, v79
	v_mfma_f32_32x32x16_bf16 v[16:31], v[122:125], v[48:51], v[16:31]
	s_mov_b64 s[14:15], -1
	s_and_b64 vcc, exec, s[40:41]
	v_add_f32_e32 v32, v32, v64
	v_add_f32_e32 v33, v33, v65
	v_add_f32_e32 v34, v34, v66
	v_add_f32_e32 v35, v35, v67
	v_add_f32_e32 v32, v32, v68
	v_add_f32_e32 v33, v33, v69
	v_add_f32_e32 v34, v34, v70
	v_add_f32_e32 v35, v35, v71
	v_cvt_pk_bf16_f32 v48, v64, v65
	v_cvt_pk_bf16_f32 v49, v66, v67
	v_cvt_pk_bf16_f32 v50, v68, v69
	v_cvt_pk_bf16_f32 v51, v70, v71
	s_nop 0
	v_mfma_f32_32x32x16_bf16 v[0:15], v[118:121], v[48:51], v[0:15]
	v_mfma_f32_32x32x16_bf16 v[16:31], v[114:117], v[48:51], v[16:31]
	v_add_f32_e32 v32, v32, v72
	v_add_f32_e32 v33, v33, v73
	v_add_f32_e32 v34, v34, v74
	v_add_f32_e32 v35, v35, v75
	v_add_f32_e32 v32, v32, v76
	v_add_f32_e32 v33, v33, v77
	v_add_f32_e32 v34, v34, v78
	v_add_f32_e32 v35, v35, v79
	v_cvt_pk_bf16_f32 v48, v72, v73
	v_cvt_pk_bf16_f32 v49, v74, v75
	v_cvt_pk_bf16_f32 v50, v76, v77
	v_cvt_pk_bf16_f32 v51, v78, v79
	s_nop 0
	v_mfma_f32_32x32x16_bf16 v[0:15], v[110:113], v[48:51], v[0:15]
	v_mfma_f32_32x32x16_bf16 v[16:31], v[106:109], v[48:51], v[16:31]
	s_cbranch_vccz .LBB0_108
	s_waitcnt vmcnt(2)
	s_mov_b64 s[14:15], 0

.LBB0_117:
	s_lshl_b64 s[14:15], s[4:5], 17
	s_lshl_b32 s4, s43, 13
	v_lshl_add_u64 v[48:49], v[146:147], 0, s[14:15]
	s_add_i32 s4, s33, s4
	v_lshl_add_u64 v[48:49], v[48:49], 0, s[20:21]
	s_add_i32 m0, s4, 0x9000
	s_sub_i32 s4, s49, 63
	global_load_lds_dwordx4 v[48:49], off
	s_cmp_gt_i32 s4, s48
	s_cbranch_scc1 .LBB0_125
	s_mul_i32 s4, s52, 0x3000
	s_add_i32 s4, s4, 16
	v_add_u32_e32 v52, s4, v149
	ds_read_b128 v[48:51], v52
	ds_read_b128 v[106:109], v52 offset:32
	ds_read_b128 v[64:67], v52 offset:6144
	ds_read_b128 v[110:113], v52 offset:6176
	ds_read_b128 v[114:117], v52 offset:64
	ds_read_b128 v[118:121], v52 offset:96
	ds_read_b128 v[122:125], v52 offset:6208
	ds_read_b128 v[126:129], v52 offset:6240
	v_add_u32_e32 v52, s4, v150
	ds_read_b128 v[130:133], v52
	ds_read_b128 v[134:137], v52 offset:6144
	v_add_u32_e32 v52, s4, v151
	ds_read_b128 v[162:165], v52
	ds_read_b128 v[166:169], v52 offset:6144
	s_waitcnt lgkmcnt(0)
	v_mfma_f32_32x32x16_bf16 v[48:63], v[48:51], v[82:85], 0
	v_mfma_f32_32x32x16_bf16 v[64:79], v[64:67], v[82:85], 0
	v_mfma_f32_32x32x16_bf16 v[48:63], v[106:109], v[86:89], v[48:63]
	v_mfma_f32_32x32x16_bf16 v[64:79], v[110:113], v[86:89], v[64:79]
	v_mfma_f32_32x32x16_bf16 v[48:63], v[114:117], v[90:93], v[48:63]
	v_mfma_f32_32x32x16_bf16 v[64:79], v[122:125], v[90:93], v[64:79]
	v_mfma_f32_32x32x16_bf16 v[48:63], v[118:121], v[94:97], v[48:63]
	v_mfma_f32_32x32x16_bf16 v[64:79], v[126:129], v[94:97], v[64:79]
	v_mfma_f32_32x32x16_bf16 v[48:63], v[130:133], v[98:101], v[48:63]
	v_mfma_f32_32x32x16_bf16 v[64:79], v[134:137], v[98:101], v[64:79]
	v_mfma_f32_32x32x16_bf16 v[48:63], v[162:165], v[102:105], v[48:63]
	v_mfma_f32_32x32x16_bf16 v[64:79], v[166:169], v[102:105], v[64:79]
	v_lshl_add_u32 v108, s52, 13, v160
	ds_read_b64_tr_b16 v[134:135], v108 offset:0
	ds_read_b64_tr_b16 v[136:137], v108 offset:1024
	ds_read_b64_tr_b16 v[130:131], v108 offset:64
	ds_read_b64_tr_b16 v[132:133], v108 offset:1088
	ds_read_b64_tr_b16 v[126:127], v108 offset:2048
	ds_read_b64_tr_b16 v[128:129], v108 offset:3072
	ds_read_b64_tr_b16 v[122:123], v108 offset:2112
	ds_read_b64_tr_b16 v[124:125], v108 offset:3136
	ds_read_b64_tr_b16 v[118:119], v108 offset:4096
	ds_read_b64_tr_b16 v[120:121], v108 offset:5120
	ds_read_b64_tr_b16 v[114:115], v108 offset:4160
	ds_read_b64_tr_b16 v[116:117], v108 offset:5184
	ds_read_b64_tr_b16 v[110:111], v108 offset:6144
	ds_read_b64_tr_b16 v[112:113], v108 offset:7168
	ds_read_b64_tr_b16 v[106:107], v108 offset:6208
	ds_read_b64_tr_b16 v[108:109], v108 offset:7232
	s_cmp_le_i32 s49, s34
	s_cbranch_scc1 .LBB0_120
	v_add_u32_e32 v161, s49, v148
	v_subrev_u32_e32 v163, 31, v161
	v_subrev_u32_e32 v162, 63, v161
	v_cmp_le_i32_e32 vcc, v163, v142
	s_nop 3
	v_cndmask_b32_e32 v64, v198, v64, vcc
	v_cmp_lt_i32_e32 vcc, v162, v142
	s_nop 1
	v_cndmask_b32_e32 v49, v198, v49, vcc
	v_cmp_le_i32_e32 vcc, v162, v142
	v_subrev_u32_e32 v162, 30, v161
	s_nop 0
	v_cndmask_b32_e32 v48, v198, v48, vcc
	v_cmp_le_i32_e32 vcc, v162, v142
	v_subrev_u32_e32 v162, 61, v161
	s_nop 0
	v_cndmask_b32_e32 v65, v198, v65, vcc
	v_cmp_le_i32_e32 vcc, v162, v142
	v_subrev_u32_e32 v162, 29, v161
	s_nop 0
	v_cndmask_b32_e32 v50, v198, v50, vcc
	v_cmp_le_i32_e32 vcc, v162, v142
	v_subrev_u32_e32 v162, 60, v161
	s_nop 0
	v_cndmask_b32_e32 v66, v198, v66, vcc
	v_cmp_le_i32_e32 vcc, v162, v142
	v_subrev_u32_e32 v162, 28, v161
	s_nop 0
	v_cndmask_b32_e32 v51, v198, v51, vcc
	v_cmp_le_i32_e32 vcc, v162, v142
	v_subrev_u32_e32 v162, 55, v161
	s_nop 0
	v_cndmask_b32_e32 v67, v198, v67, vcc
	v_cmp_le_i32_e32 vcc, v162, v142
	v_subrev_u32_e32 v162, 23, v161
	s_nop 0
	v_cndmask_b32_e32 v52, v198, v52, vcc
	v_cmp_le_i32_e32 vcc, v162, v142
	v_subrev_u32_e32 v162, 54, v161
	s_nop 0
	v_cndmask_b32_e32 v68, v198, v68, vcc
	v_cmp_le_i32_e32 vcc, v162, v142
	v_subrev_u32_e32 v162, 22, v161
	s_nop 0
	v_cndmask_b32_e32 v53, v198, v53, vcc
	v_cmp_le_i32_e32 vcc, v162, v142
	v_subrev_u32_e32 v162, 53, v161
	s_nop 0
	v_cndmask_b32_e32 v69, v198, v69, vcc
	v_cmp_le_i32_e32 vcc, v162, v142
	v_subrev_u32_e32 v162, 21, v161
	s_nop 0
	v_cndmask_b32_e32 v54, v198, v54, vcc
	v_cmp_le_i32_e32 vcc, v162, v142
	v_subrev_u32_e32 v162, 52, v161
	s_nop 0
	v_cndmask_b32_e32 v70, v198, v70, vcc
	v_cmp_le_i32_e32 vcc, v162, v142
	v_subrev_u32_e32 v162, 20, v161
	s_nop 0
	v_cndmask_b32_e32 v55, v198, v55, vcc
	v_cmp_le_i32_e32 vcc, v162, v142
	v_subrev_u32_e32 v162, 47, v161
	s_nop 0
	v_cndmask_b32_e32 v71, v198, v71, vcc
	v_cmp_le_i32_e32 vcc, v162, v142
	v_add_u32_e32 v162, -15, v161
	s_nop 0
	v_cndmask_b32_e32 v56, v198, v56, vcc
	v_cmp_le_i32_e32 vcc, v162, v142
	v_subrev_u32_e32 v162, 46, v161
	s_nop 0
	v_cndmask_b32_e32 v72, v198, v72, vcc
	v_cmp_le_i32_e32 vcc, v162, v142
	v_add_u32_e32 v162, -14, v161
	s_nop 0
	v_cndmask_b32_e32 v57, v198, v57, vcc
	v_cmp_le_i32_e32 vcc, v162, v142
	v_subrev_u32_e32 v162, 45, v161
	s_nop 0
	v_cndmask_b32_e32 v73, v198, v73, vcc
	v_cmp_le_i32_e32 vcc, v162, v142
	v_add_u32_e32 v162, -13, v161
	s_nop 0
	v_cndmask_b32_e32 v58, v198, v58, vcc
	v_cmp_le_i32_e32 vcc, v162, v142
	v_subrev_u32_e32 v162, 44, v161
	s_nop 0
	v_cndmask_b32_e32 v74, v198, v74, vcc
	v_cmp_le_i32_e32 vcc, v162, v142
	v_add_u32_e32 v162, -12, v161
	s_nop 0
	v_cndmask_b32_e32 v59, v198, v59, vcc
	v_cmp_le_i32_e32 vcc, v162, v142
	v_subrev_u32_e32 v162, 39, v161
	s_nop 0
	v_cndmask_b32_e32 v75, v198, v75, vcc
	v_cmp_le_i32_e32 vcc, v162, v142
	v_add_u32_e32 v162, -7, v161
	s_nop 0
	v_cndmask_b32_e32 v60, v198, v60, vcc
	v_cmp_le_i32_e32 vcc, v162, v142
	v_subrev_u32_e32 v162, 38, v161
	s_nop 0
	v_cndmask_b32_e32 v76, v198, v76, vcc
	v_cmp_le_i32_e32 vcc, v162, v142
	v_add_u32_e32 v162, -6, v161
	s_nop 0
	v_cndmask_b32_e32 v61, v198, v61, vcc
	v_cmp_le_i32_e32 vcc, v162, v142
	v_subrev_u32_e32 v162, 37, v161
	s_nop 0
	v_cndmask_b32_e32 v77, v198, v77, vcc
	v_cmp_le_i32_e32 vcc, v162, v142
	v_add_u32_e32 v162, -5, v161
	s_nop 0
	v_cndmask_b32_e32 v62, v198, v62, vcc
	v_cmp_le_i32_e32 vcc, v162, v142
	v_subrev_u32_e32 v162, 36, v161
	v_add_u32_e32 v161, -4, v161
	v_cndmask_b32_e32 v78, v198, v78, vcc
	v_cmp_le_i32_e32 vcc, v162, v142
	s_nop 1
	v_cndmask_b32_e32 v63, v198, v63, vcc
	v_cmp_le_i32_e32 vcc, v161, v142
	s_nop 1
	v_cndmask_b32_e32 v79, v198, v79, vcc

.LBB0_863:
	s_add_i32 s53, 16, 0x10000
	v_add_u32_e32 v150, s53, v149
	ds_read_b128 v[160:163], v150
	ds_read_b128 v[164:167], v150 offset:1024
	ds_read_b128 v[168:171], v150 offset:2048
	ds_read_b128 v[172:175], v150 offset:3072
	s_add_i32 s52, s52, 2
	v_lshl_add_u64 v[150:151], v[144:145], 0, s[42:43]
	v_add_u32_e32 v250, 16, v148
	v_lshl_add_u64 v[208:209], v[150:151], 0, s[20:21]
	s_add_i32 m0, s36, 0xc000
	ds_read_b128 v[176:179], v250
	ds_read_b128 v[180:183], v250 offset:1024
	ds_read_b128 v[184:187], v250 offset:2048
	ds_read_b128 v[188:191], v250 offset:3072
	ds_read_b128 v[204:207], v250 offset:4096
	ds_read_b128 v[214:217], v250 offset:5120
	ds_read_b128 v[218:221], v250 offset:6144
	ds_read_b128 v[222:225], v250 offset:7168
	global_load_lds_dwordx4 v[208:209], off
	v_lshl_add_u64 v[208:209], v[146:147], 0, s[42:43]
	v_lshl_add_u64 v[226:227], v[208:209], 0, s[20:21]
	s_add_i32 m0, s36, 0xe000
	s_nop 0
	global_load_lds_dwordx4 v[226:227], off
	s_waitcnt lgkmcnt(8)
	s_barrier
	s_waitcnt lgkmcnt(0)
	s_waitcnt lgkmcnt(0)
	v_mfma_f32_16x16x32_bf16 v[128:131], v[160:163], v[176:179], v[128:131]
	v_mfma_f32_16x16x32_bf16 v[124:127], v[168:171], v[176:179], v[124:127]
	v_mfma_f32_16x16x32_bf16 v[112:115], v[160:163], v[184:187], v[112:115]
	v_mfma_f32_16x16x32_bf16 v[108:111], v[168:171], v[184:187], v[108:111]
	v_mfma_f32_16x16x32_bf16 v[96:99], v[160:163], v[204:207], v[96:99]
	v_mfma_f32_16x16x32_bf16 v[92:95], v[168:171], v[204:207], v[92:95]
	v_mfma_f32_16x16x32_bf16 v[76:79], v[160:163], v[218:221], v[76:79]
	v_mfma_f32_16x16x32_bf16 v[72:75], v[168:171], v[218:221], v[72:75]
	v_mfma_f32_16x16x32_bf16 v[128:131], v[164:167], v[180:183], v[128:131]
	v_mfma_f32_16x16x32_bf16 v[124:127], v[172:175], v[180:183], v[124:127]
	v_mfma_f32_16x16x32_bf16 v[112:115], v[164:167], v[188:191], v[112:115]
	v_mfma_f32_16x16x32_bf16 v[108:111], v[172:175], v[188:191], v[108:111]
	v_mfma_f32_16x16x32_bf16 v[96:99], v[164:167], v[214:217], v[96:99]
	v_mfma_f32_16x16x32_bf16 v[92:95], v[172:175], v[214:217], v[92:95]
	v_mfma_f32_16x16x32_bf16 v[76:79], v[164:167], v[222:225], v[76:79]
	v_mfma_f32_16x16x32_bf16 v[72:75], v[172:175], v[222:225], v[72:75]
	s_barrier
	s_add_i32 s54, 16, 0x14000
	v_lshl_add_u64 v[242:243], v[134:135], 0, s[42:43]
	s_add_i32 s53, s53, s37
	v_add_u32_e32 v210, s54, v149
	v_lshl_add_u64 v[244:245], v[242:243], 0, s[64:65]
	s_mov_b32 m0, s53
	ds_read_b128 v[226:229], v210
	ds_read_b128 v[230:233], v210 offset:1024
	ds_read_b128 v[234:237], v210 offset:2048
	ds_read_b128 v[238:241], v210 offset:3072
	global_load_lds_dwordx4 v[244:245], off
	v_lshl_add_u64 v[244:245], v[136:137], 0, s[42:43]
	v_lshl_add_u64 v[246:247], v[244:245], 0, s[64:65]
	s_add_i32 m0, s53, 0x2000
	s_nop 0
	global_load_lds_dwordx4 v[246:247], off
	s_barrier
	s_waitcnt lgkmcnt(0)
	s_waitcnt lgkmcnt(0)
	v_mfma_f32_16x16x32_bf16 v[120:123], v[226:229], v[176:179], v[120:123]
	v_mfma_f32_16x16x32_bf16 v[116:119], v[234:237], v[176:179], v[116:119]
	v_mfma_f32_16x16x32_bf16 v[104:107], v[226:229], v[184:187], v[104:107]
	v_mfma_f32_16x16x32_bf16 v[100:103], v[234:237], v[184:187], v[100:103]
	v_mfma_f32_16x16x32_bf16 v[88:91], v[226:229], v[204:207], v[88:91]
	v_mfma_f32_16x16x32_bf16 v[84:87], v[234:237], v[204:207], v[84:87]
	v_mfma_f32_16x16x32_bf16 v[68:71], v[226:229], v[218:221], v[68:71]
	v_mfma_f32_16x16x32_bf16 v[64:67], v[234:237], v[218:221], v[64:67]
	v_mfma_f32_16x16x32_bf16 v[120:123], v[230:233], v[180:183], v[120:123]
	v_mfma_f32_16x16x32_bf16 v[116:119], v[238:241], v[180:183], v[116:119]
	v_mfma_f32_16x16x32_bf16 v[104:107], v[230:233], v[188:191], v[104:107]
	v_mfma_f32_16x16x32_bf16 v[100:103], v[238:241], v[188:191], v[100:103]
	v_mfma_f32_16x16x32_bf16 v[88:91], v[230:233], v[214:217], v[88:91]
	v_mfma_f32_16x16x32_bf16 v[84:87], v[238:241], v[214:217], v[84:87]
	v_mfma_f32_16x16x32_bf16 v[68:71], v[230:233], v[222:225], v[68:71]
	v_mfma_f32_16x16x32_bf16 v[64:67], v[238:241], v[222:225], v[64:67]
	v_lshl_add_u64 v[246:247], v[142:143], 0, s[42:43]
	s_mov_b32 m0, s36
	v_lshl_add_u64 v[248:249], v[246:247], 0, s[64:65]
	s_barrier
	ds_read_b128 v[176:179], v250 offset:16384
	ds_read_b128 v[180:183], v250 offset:17408
	ds_read_b128 v[184:187], v250 offset:18432
	ds_read_b128 v[188:191], v250 offset:19456
	ds_read_b128 v[204:207], v250 offset:20480
	ds_read_b128 v[214:217], v250 offset:21504
	ds_read_b128 v[218:221], v250 offset:22528
	ds_read_b128 v[222:225], v250 offset:23552
	global_load_lds_dwordx4 v[248:249], off
	v_lshl_add_u64 v[248:249], v[132:133], 0, s[42:43]
	v_lshl_add_u64 v[210:211], v[248:249], 0, s[64:65]
	s_add_i32 m0, s36, 0x2000
	s_nop 0
	global_load_lds_dwordx4 v[210:211], off
	s_barrier
	s_waitcnt lgkmcnt(0)
	s_waitcnt lgkmcnt(0)
	v_mfma_f32_16x16x32_bf16 v[60:63], v[160:163], v[176:179], v[60:63]
	v_mfma_f32_16x16x32_bf16 v[56:59], v[168:171], v[176:179], v[56:59]
	v_mfma_f32_16x16x32_bf16 v[44:47], v[160:163], v[184:187], v[44:47]
	v_mfma_f32_16x16x32_bf16 v[40:43], v[168:171], v[184:187], v[40:43]
	v_mfma_f32_16x16x32_bf16 v[28:31], v[160:163], v[204:207], v[28:31]
	v_mfma_f32_16x16x32_bf16 v[24:27], v[168:171], v[204:207], v[24:27]
	v_mfma_f32_16x16x32_bf16 v[12:15], v[160:163], v[218:221], v[12:15]
	v_mfma_f32_16x16x32_bf16 v[8:11], v[168:171], v[218:221], v[8:11]
	v_mfma_f32_16x16x32_bf16 v[60:63], v[164:167], v[180:183], v[60:63]
	v_mfma_f32_16x16x32_bf16 v[56:59], v[172:175], v[180:183], v[56:59]
	v_mfma_f32_16x16x32_bf16 v[44:47], v[164:167], v[188:191], v[44:47]
	v_mfma_f32_16x16x32_bf16 v[40:43], v[172:175], v[188:191], v[40:43]
	v_mfma_f32_16x16x32_bf16 v[28:31], v[164:167], v[214:217], v[28:31]
	v_mfma_f32_16x16x32_bf16 v[24:27], v[172:175], v[214:217], v[24:27]
	v_mfma_f32_16x16x32_bf16 v[12:15], v[164:167], v[222:225], v[12:15]
	v_mfma_f32_16x16x32_bf16 v[8:11], v[172:175], v[222:225], v[8:11]
	s_barrier
	v_lshl_add_u64 v[210:211], v[138:139], 0, s[42:43]
	s_add_i32 s53, s54, s37
	v_lshl_add_u64 v[160:161], v[210:211], 0, s[64:65]
	s_mov_b32 m0, s53
	v_lshl_add_u64 v[212:213], v[140:141], 0, s[42:43]
	global_load_lds_dwordx4 v[160:161], off
	v_lshl_add_u64 v[160:161], v[212:213], 0, s[64:65]
	s_add_i32 m0, s53, 0x2000
	s_nop 0
	global_load_lds_dwordx4 v[160:161], off
	s_waitcnt vmcnt(6)
	s_barrier
	v_mfma_f32_16x16x32_bf16 v[52:55], v[226:229], v[176:179], v[52:55]
	v_mfma_f32_16x16x32_bf16 v[48:51], v[234:237], v[176:179], v[48:51]
	v_mfma_f32_16x16x32_bf16 v[36:39], v[226:229], v[184:187], v[36:39]
	v_mfma_f32_16x16x32_bf16 v[32:35], v[234:237], v[184:187], v[32:35]
	v_mfma_f32_16x16x32_bf16 v[20:23], v[226:229], v[204:207], v[20:23]
	v_mfma_f32_16x16x32_bf16 v[16:19], v[234:237], v[204:207], v[16:19]
	v_mfma_f32_16x16x32_bf16 v[4:7], v[226:229], v[218:221], v[4:7]
	v_mfma_f32_16x16x32_bf16 v[0:3], v[234:237], v[218:221], v[0:3]
	v_mfma_f32_16x16x32_bf16 v[52:55], v[230:233], v[180:183], v[52:55]
	v_mfma_f32_16x16x32_bf16 v[48:51], v[238:241], v[180:183], v[48:51]
	v_mfma_f32_16x16x32_bf16 v[36:39], v[230:233], v[188:191], v[36:39]
	v_mfma_f32_16x16x32_bf16 v[32:35], v[238:241], v[188:191], v[32:35]
	v_mfma_f32_16x16x32_bf16 v[20:23], v[230:233], v[214:217], v[20:23]
	v_mfma_f32_16x16x32_bf16 v[16:19], v[238:241], v[214:217], v[16:19]
	v_mfma_f32_16x16x32_bf16 v[4:7], v[230:233], v[222:225], v[4:7]
	v_mfma_f32_16x16x32_bf16 v[0:3], v[238:241], v[222:225], v[0:3]
	s_add_i32 s53, 16, 0x18000
	v_add_u32_e32 v172, s53, v149
	s_barrier
	ds_read_b128 v[160:163], v172
	ds_read_b128 v[164:167], v172 offset:1024
	ds_read_b128 v[168:171], v172 offset:2048
	ds_read_b128 v[172:175], v172 offset:3072
	v_lshl_add_u64 v[150:151], v[150:151], 0, s[64:65]
	s_add_i32 m0, s36, 0x4000
	ds_read_b128 v[176:179], v250 offset:32768
	ds_read_b128 v[180:183], v250 offset:33792
	ds_read_b128 v[184:187], v250 offset:34816
	ds_read_b128 v[188:191], v250 offset:35840
	ds_read_b128 v[204:207], v250 offset:36864
	ds_read_b128 v[214:217], v250 offset:37888
	ds_read_b128 v[218:221], v250 offset:38912
	ds_read_b128 v[222:225], v250 offset:39936
	global_load_lds_dwordx4 v[150:151], off
	v_lshl_add_u64 v[150:151], v[208:209], 0, s[64:65]
	s_add_i32 m0, s36, 0x6000
	s_nop 0
	global_load_lds_dwordx4 v[150:151], off
	s_waitcnt lgkmcnt(8)
	s_barrier
	s_waitcnt lgkmcnt(0)
	s_waitcnt lgkmcnt(0)
	v_mfma_f32_16x16x32_bf16 v[128:131], v[160:163], v[176:179], v[128:131]
	v_mfma_f32_16x16x32_bf16 v[124:127], v[168:171], v[176:179], v[124:127]
	v_mfma_f32_16x16x32_bf16 v[112:115], v[160:163], v[184:187], v[112:115]
	v_mfma_f32_16x16x32_bf16 v[108:111], v[168:171], v[184:187], v[108:111]
	v_mfma_f32_16x16x32_bf16 v[96:99], v[160:163], v[204:207], v[96:99]
	v_mfma_f32_16x16x32_bf16 v[92:95], v[168:171], v[204:207], v[92:95]
	v_mfma_f32_16x16x32_bf16 v[76:79], v[160:163], v[218:221], v[76:79]
	v_mfma_f32_16x16x32_bf16 v[72:75], v[168:171], v[218:221], v[72:75]
	v_mfma_f32_16x16x32_bf16 v[128:131], v[164:167], v[180:183], v[128:131]
	v_mfma_f32_16x16x32_bf16 v[124:127], v[172:175], v[180:183], v[124:127]
	v_mfma_f32_16x16x32_bf16 v[112:115], v[164:167], v[188:191], v[112:115]
	v_mfma_f32_16x16x32_bf16 v[108:111], v[172:175], v[188:191], v[108:111]
	v_mfma_f32_16x16x32_bf16 v[96:99], v[164:167], v[214:217], v[96:99]
	v_mfma_f32_16x16x32_bf16 v[92:95], v[172:175], v[214:217], v[92:95]
	v_mfma_f32_16x16x32_bf16 v[76:79], v[164:167], v[222:225], v[76:79]
	v_mfma_f32_16x16x32_bf16 v[72:75], v[172:175], v[222:225], v[72:75]
	s_barrier
	s_add_i32 s54, 16, 0x1c000
	v_add_u32_e32 v150, s54, v149
	s_add_i32 s53, s53, s37
	ds_read_b128 v[226:229], v150
	ds_read_b128 v[230:233], v150 offset:1024
	ds_read_b128 v[234:237], v150 offset:2048
	ds_read_b128 v[238:241], v150 offset:3072
	v_lshl_add_u64 v[150:151], v[242:243], 0, s[68:69]
	s_mov_b32 m0, s53
	s_nop 0
	global_load_lds_dwordx4 v[150:151], off
	v_lshl_add_u64 v[150:151], v[244:245], 0, s[68:69]
	s_add_i32 m0, s53, 0x2000
	s_nop 0
	global_load_lds_dwordx4 v[150:151], off
	s_barrier
	s_waitcnt lgkmcnt(0)
	s_waitcnt lgkmcnt(0)
	v_mfma_f32_16x16x32_bf16 v[120:123], v[226:229], v[176:179], v[120:123]
	v_mfma_f32_16x16x32_bf16 v[116:119], v[234:237], v[176:179], v[116:119]
	v_mfma_f32_16x16x32_bf16 v[104:107], v[226:229], v[184:187], v[104:107]
	v_mfma_f32_16x16x32_bf16 v[100:103], v[234:237], v[184:187], v[100:103]
	v_mfma_f32_16x16x32_bf16 v[88:91], v[226:229], v[204:207], v[88:91]
	v_mfma_f32_16x16x32_bf16 v[84:87], v[234:237], v[204:207], v[84:87]
	v_mfma_f32_16x16x32_bf16 v[68:71], v[226:229], v[218:221], v[68:71]
	v_mfma_f32_16x16x32_bf16 v[64:67], v[234:237], v[218:221], v[64:67]
	v_mfma_f32_16x16x32_bf16 v[120:123], v[230:233], v[180:183], v[120:123]
	v_mfma_f32_16x16x32_bf16 v[116:119], v[238:241], v[180:183], v[116:119]
	v_mfma_f32_16x16x32_bf16 v[104:107], v[230:233], v[188:191], v[104:107]
	v_mfma_f32_16x16x32_bf16 v[100:103], v[238:241], v[188:191], v[100:103]
	v_mfma_f32_16x16x32_bf16 v[88:91], v[230:233], v[214:217], v[88:91]
	v_mfma_f32_16x16x32_bf16 v[84:87], v[238:241], v[214:217], v[84:87]
	v_mfma_f32_16x16x32_bf16 v[68:71], v[230:233], v[222:225], v[68:71]
	v_mfma_f32_16x16x32_bf16 v[64:67], v[238:241], v[222:225], v[64:67]
	s_mov_b32 m0, s41
	v_lshl_add_u64 v[150:151], v[246:247], 0, s[68:69]
	s_barrier
	ds_read_b128 v[176:179], v250 offset:49152
	ds_read_b128 v[180:183], v250 offset:50176
	ds_read_b128 v[184:187], v250 offset:51200
	ds_read_b128 v[188:191], v250 offset:52224
	ds_read_b128 v[204:207], v250 offset:53248
	ds_read_b128 v[214:217], v250 offset:54272
	ds_read_b128 v[218:221], v250 offset:55296
	ds_read_b128 v[222:225], v250 offset:56320
	global_load_lds_dwordx4 v[150:151], off
	v_lshl_add_u64 v[150:151], v[248:249], 0, s[68:69]
	s_mov_b32 m0, s50
	s_nop 0
	global_load_lds_dwordx4 v[150:151], off
	s_barrier
	s_waitcnt lgkmcnt(0)
	s_waitcnt lgkmcnt(0)
	v_mfma_f32_16x16x32_bf16 v[60:63], v[160:163], v[176:179], v[60:63]
	v_mfma_f32_16x16x32_bf16 v[56:59], v[168:171], v[176:179], v[56:59]
	v_mfma_f32_16x16x32_bf16 v[44:47], v[160:163], v[184:187], v[44:47]
	v_mfma_f32_16x16x32_bf16 v[40:43], v[168:171], v[184:187], v[40:43]
	v_mfma_f32_16x16x32_bf16 v[28:31], v[160:163], v[204:207], v[28:31]
	v_mfma_f32_16x16x32_bf16 v[24:27], v[168:171], v[204:207], v[24:27]
	v_mfma_f32_16x16x32_bf16 v[12:15], v[160:163], v[218:221], v[12:15]
	v_mfma_f32_16x16x32_bf16 v[8:11], v[168:171], v[218:221], v[8:11]
	v_mfma_f32_16x16x32_bf16 v[60:63], v[164:167], v[180:183], v[60:63]
	v_mfma_f32_16x16x32_bf16 v[56:59], v[172:175], v[180:183], v[56:59]
	v_mfma_f32_16x16x32_bf16 v[44:47], v[164:167], v[188:191], v[44:47]
	v_mfma_f32_16x16x32_bf16 v[40:43], v[172:175], v[188:191], v[40:43]
	v_mfma_f32_16x16x32_bf16 v[28:31], v[164:167], v[214:217], v[28:31]
	v_mfma_f32_16x16x32_bf16 v[24:27], v[172:175], v[214:217], v[24:27]
	v_mfma_f32_16x16x32_bf16 v[12:15], v[164:167], v[222:225], v[12:15]
	v_mfma_f32_16x16x32_bf16 v[8:11], v[172:175], v[222:225], v[8:11]
	s_barrier
	s_add_i32 s53, s54, s37
	v_lshl_add_u64 v[150:151], v[210:211], 0, s[68:69]
	s_mov_b32 m0, s53
	s_nop 0
	global_load_lds_dwordx4 v[150:151], off
	v_lshl_add_u64 v[150:151], v[212:213], 0, s[68:69]
	s_add_i32 m0, s53, 0x2000
	s_nop 0
	global_load_lds_dwordx4 v[150:151], off
	s_waitcnt vmcnt(6)
	s_barrier
	v_mfma_f32_16x16x32_bf16 v[52:55], v[226:229], v[176:179], v[52:55]
	v_mfma_f32_16x16x32_bf16 v[48:51], v[234:237], v[176:179], v[48:51]
	v_mfma_f32_16x16x32_bf16 v[36:39], v[226:229], v[184:187], v[36:39]
	v_mfma_f32_16x16x32_bf16 v[32:35], v[234:237], v[184:187], v[32:35]
	v_mfma_f32_16x16x32_bf16 v[20:23], v[226:229], v[204:207], v[20:23]
	v_mfma_f32_16x16x32_bf16 v[16:19], v[234:237], v[204:207], v[16:19]
	v_mfma_f32_16x16x32_bf16 v[4:7], v[226:229], v[218:221], v[4:7]
	v_mfma_f32_16x16x32_bf16 v[0:3], v[234:237], v[218:221], v[0:3]
	v_mfma_f32_16x16x32_bf16 v[52:55], v[230:233], v[180:183], v[52:55]
	v_mfma_f32_16x16x32_bf16 v[48:51], v[238:241], v[180:183], v[48:51]
	v_mfma_f32_16x16x32_bf16 v[36:39], v[230:233], v[188:191], v[36:39]
	v_mfma_f32_16x16x32_bf16 v[32:35], v[238:241], v[188:191], v[32:35]
	v_mfma_f32_16x16x32_bf16 v[20:23], v[230:233], v[214:217], v[20:23]
	v_mfma_f32_16x16x32_bf16 v[16:19], v[238:241], v[214:217], v[16:19]
	v_mfma_f32_16x16x32_bf16 v[4:7], v[230:233], v[222:225], v[4:7]
	v_mfma_f32_16x16x32_bf16 v[0:3], v[238:241], v[222:225], v[0:3]
	s_add_u32 s42, s42, 0x100
	s_addc_u32 s43, s43, 0
	s_cmp_ge_i32 s52, s51
	s_barrier
	s_cbranch_scc0 .LBB0_863
.LBB0_864:
	s_ashr_i32 s41, s40, 31
	s_lshl_b64 s[42:43], s[40:41], 7
	s_add_u32 s37, s46, s42
	s_addc_u32 s41, s47, s43
	s_add_u32 s37, s37, s4
	s_addc_u32 s41, s41, 0
	s_add_u32 s42, s37, 0xffffff80
	v_add_u32_e32 v208, 16, v149
	s_addc_u32 s43, s41, -1
	v_add_u32_e32 v144, 0x10000, v208
	v_add_u32_e32 v209, 16, v148
	v_lshl_add_u64 v[188:189], s[42:43], 0, v[80:81]
	s_add_i32 m0, s36, 0xc000
	ds_read_b128 v[132:135], v144
	ds_read_b128 v[136:139], v144 offset:1024
	ds_read_b128 v[140:143], v144 offset:2048
	ds_read_b128 v[144:147], v144 offset:3072
	ds_read_b128 v[148:151], v209
	ds_read_b128 v[160:163], v209 offset:1024
	ds_read_b128 v[164:167], v209 offset:2048
	ds_read_b128 v[168:171], v209 offset:3072
	ds_read_b128 v[172:175], v209 offset:4096
	ds_read_b128 v[176:179], v209 offset:5120
	ds_read_b128 v[180:183], v209 offset:6144
	ds_read_b128 v[184:187], v209 offset:7168
	global_load_lds_dwordx4 v[188:189], off
	v_lshl_add_u64 v[82:83], s[42:43], 0, v[82:83]
	s_add_i32 m0, s36, 0xe000
	s_nop 0
	global_load_lds_dwordx4 v[82:83], off
	s_barrier
	s_waitcnt lgkmcnt(0)
	s_waitcnt lgkmcnt(0)
	v_mfma_f32_16x16x32_bf16 v[128:131], v[132:135], v[148:151], v[128:131]
	v_mfma_f32_16x16x32_bf16 v[124:127], v[140:143], v[148:151], v[124:127]
	v_mfma_f32_16x16x32_bf16 v[112:115], v[132:135], v[164:167], v[112:115]
	v_mfma_f32_16x16x32_bf16 v[108:111], v[140:143], v[164:167], v[108:111]
	v_mfma_f32_16x16x32_bf16 v[96:99], v[132:135], v[172:175], v[96:99]
	v_mfma_f32_16x16x32_bf16 v[92:95], v[140:143], v[172:175], v[92:95]
	v_mfma_f32_16x16x32_bf16 v[76:79], v[132:135], v[180:183], v[76:79]
	v_mfma_f32_16x16x32_bf16 v[72:75], v[140:143], v[180:183], v[72:75]
	v_mfma_f32_16x16x32_bf16 v[128:131], v[136:139], v[160:163], v[128:131]
	v_mfma_f32_16x16x32_bf16 v[124:127], v[144:147], v[160:163], v[124:127]
	v_mfma_f32_16x16x32_bf16 v[112:115], v[136:139], v[168:171], v[112:115]
	v_mfma_f32_16x16x32_bf16 v[108:111], v[144:147], v[168:171], v[108:111]
	v_mfma_f32_16x16x32_bf16 v[96:99], v[136:139], v[176:179], v[96:99]
	v_mfma_f32_16x16x32_bf16 v[92:95], v[144:147], v[176:179], v[92:95]
	v_mfma_f32_16x16x32_bf16 v[76:79], v[136:139], v[184:187], v[76:79]
	v_mfma_f32_16x16x32_bf16 v[72:75], v[144:147], v[184:187], v[72:75]
	v_add_u32_e32 v80, 0x14000, v208
	s_barrier
	ds_read_b128 v[188:191], v80
	ds_read_b128 v[204:207], v80 offset:1024
	ds_read_b128 v[214:217], v80 offset:2048
	ds_read_b128 v[218:221], v80 offset:3072
	s_barrier
	s_waitcnt lgkmcnt(0)
	s_waitcnt lgkmcnt(0)
	v_mfma_f32_16x16x32_bf16 v[120:123], v[188:191], v[148:151], v[120:123]
	v_mfma_f32_16x16x32_bf16 v[116:119], v[214:217], v[148:151], v[116:119]
	v_mfma_f32_16x16x32_bf16 v[104:107], v[188:191], v[164:167], v[104:107]
	v_mfma_f32_16x16x32_bf16 v[100:103], v[214:217], v[164:167], v[100:103]
	v_mfma_f32_16x16x32_bf16 v[88:91], v[188:191], v[172:175], v[88:91]
	v_mfma_f32_16x16x32_bf16 v[82:85], v[214:217], v[172:175], v[84:87]
	v_mfma_f32_16x16x32_bf16 v[68:71], v[188:191], v[180:183], v[68:71]
	v_mfma_f32_16x16x32_bf16 v[64:67], v[214:217], v[180:183], v[64:67]
	v_mfma_f32_16x16x32_bf16 v[120:123], v[204:207], v[160:163], v[120:123]
	v_mfma_f32_16x16x32_bf16 v[116:119], v[218:221], v[160:163], v[116:119]
	v_mfma_f32_16x16x32_bf16 v[104:107], v[204:207], v[168:171], v[104:107]
	v_mfma_f32_16x16x32_bf16 v[100:103], v[218:221], v[168:171], v[100:103]
	v_mfma_f32_16x16x32_bf16 v[88:91], v[204:207], v[176:179], v[88:91]
	v_mfma_f32_16x16x32_bf16 v[82:85], v[218:221], v[176:179], v[82:85]
	v_mfma_f32_16x16x32_bf16 v[68:71], v[204:207], v[184:187], v[68:71]
	v_mfma_f32_16x16x32_bf16 v[64:67], v[218:221], v[184:187], v[64:67]
	s_barrier
	ds_read_b128 v[148:151], v209 offset:16384
	ds_read_b128 v[160:163], v209 offset:17408
	ds_read_b128 v[164:167], v209 offset:18432
	ds_read_b128 v[168:171], v209 offset:19456
	ds_read_b128 v[172:175], v209 offset:20480
	ds_read_b128 v[176:179], v209 offset:21504
	ds_read_b128 v[180:183], v209 offset:22528
	ds_read_b128 v[184:187], v209 offset:23552
	s_waitcnt vmcnt(4)
	s_barrier
	s_waitcnt lgkmcnt(0)
	s_waitcnt lgkmcnt(0)
	v_mfma_f32_16x16x32_bf16 v[60:63], v[132:135], v[148:151], v[60:63]
	v_mfma_f32_16x16x32_bf16 v[56:59], v[140:143], v[148:151], v[56:59]
	v_mfma_f32_16x16x32_bf16 v[44:47], v[132:135], v[164:167], v[44:47]
	v_mfma_f32_16x16x32_bf16 v[40:43], v[140:143], v[164:167], v[40:43]
	v_mfma_f32_16x16x32_bf16 v[28:31], v[132:135], v[172:175], v[28:31]
	v_mfma_f32_16x16x32_bf16 v[24:27], v[140:143], v[172:175], v[24:27]
	v_mfma_f32_16x16x32_bf16 v[12:15], v[132:135], v[180:183], v[12:15]
	v_mfma_f32_16x16x32_bf16 v[8:11], v[140:143], v[180:183], v[8:11]
	v_mfma_f32_16x16x32_bf16 v[60:63], v[136:139], v[160:163], v[60:63]
	v_mfma_f32_16x16x32_bf16 v[56:59], v[144:147], v[160:163], v[56:59]
	v_mfma_f32_16x16x32_bf16 v[44:47], v[136:139], v[168:171], v[44:47]
	v_mfma_f32_16x16x32_bf16 v[40:43], v[144:147], v[168:171], v[40:43]
	v_mfma_f32_16x16x32_bf16 v[28:31], v[136:139], v[176:179], v[28:31]
	v_mfma_f32_16x16x32_bf16 v[24:27], v[144:147], v[176:179], v[24:27]
	v_mfma_f32_16x16x32_bf16 v[12:15], v[136:139], v[184:187], v[12:15]
	v_mfma_f32_16x16x32_bf16 v[8:11], v[144:147], v[184:187], v[8:11]
	v_mfma_f32_16x16x32_bf16 v[52:55], v[188:191], v[148:151], v[52:55]
	v_mfma_f32_16x16x32_bf16 v[48:51], v[214:217], v[148:151], v[48:51]
	v_mfma_f32_16x16x32_bf16 v[36:39], v[188:191], v[164:167], v[36:39]
	v_mfma_f32_16x16x32_bf16 v[32:35], v[214:217], v[164:167], v[32:35]
	v_mfma_f32_16x16x32_bf16 v[20:23], v[188:191], v[172:175], v[20:23]
	v_mfma_f32_16x16x32_bf16 v[16:19], v[214:217], v[172:175], v[16:19]
	v_mfma_f32_16x16x32_bf16 v[4:7], v[188:191], v[180:183], v[4:7]
	v_mfma_f32_16x16x32_bf16 v[0:3], v[214:217], v[180:183], v[0:3]
	v_mfma_f32_16x16x32_bf16 v[52:55], v[204:207], v[160:163], v[52:55]
	v_mfma_f32_16x16x32_bf16 v[48:51], v[218:221], v[160:163], v[48:51]
	v_mfma_f32_16x16x32_bf16 v[36:39], v[204:207], v[168:171], v[36:39]
	v_mfma_f32_16x16x32_bf16 v[32:35], v[218:221], v[168:171], v[32:35]
	v_mfma_f32_16x16x32_bf16 v[20:23], v[204:207], v[176:179], v[20:23]
	v_mfma_f32_16x16x32_bf16 v[16:19], v[218:221], v[176:179], v[16:19]
	v_mfma_f32_16x16x32_bf16 v[4:7], v[204:207], v[184:187], v[4:7]
	v_mfma_f32_16x16x32_bf16 v[0:3], v[218:221], v[184:187], v[0:3]
	v_add_u32_e32 v80, 0x18000, v208
	s_barrier
	ds_read_b128 v[132:135], v80
	ds_read_b128 v[136:139], v80 offset:1024
	ds_read_b128 v[140:143], v80 offset:2048
	ds_read_b128 v[144:147], v80 offset:3072
	ds_read_b128 v[148:151], v209 offset:32768
	ds_read_b128 v[160:163], v209 offset:33792
	ds_read_b128 v[164:167], v209 offset:34816
	ds_read_b128 v[168:171], v209 offset:35840
	ds_read_b128 v[172:175], v209 offset:36864
	ds_read_b128 v[176:179], v209 offset:37888
	ds_read_b128 v[180:183], v209 offset:38912
	ds_read_b128 v[184:187], v209 offset:39936
	s_waitcnt vmcnt(2)
	s_barrier
	s_waitcnt lgkmcnt(0)
	s_waitcnt lgkmcnt(0)
	v_mfma_f32_16x16x32_bf16 v[128:131], v[132:135], v[148:151], v[128:131]
	v_mfma_f32_16x16x32_bf16 v[124:127], v[140:143], v[148:151], v[124:127]
	v_mfma_f32_16x16x32_bf16 v[112:115], v[132:135], v[164:167], v[112:115]
	v_mfma_f32_16x16x32_bf16 v[108:111], v[140:143], v[164:167], v[108:111]
	v_mfma_f32_16x16x32_bf16 v[96:99], v[132:135], v[172:175], v[96:99]
	v_mfma_f32_16x16x32_bf16 v[92:95], v[140:143], v[172:175], v[92:95]
	v_mfma_f32_16x16x32_bf16 v[76:79], v[132:135], v[180:183], v[76:79]
	v_mfma_f32_16x16x32_bf16 v[72:75], v[140:143], v[180:183], v[72:75]
	v_mfma_f32_16x16x32_bf16 v[128:131], v[136:139], v[160:163], v[128:131]
	v_mfma_f32_16x16x32_bf16 v[124:127], v[144:147], v[160:163], v[124:127]
	v_mfma_f32_16x16x32_bf16 v[112:115], v[136:139], v[168:171], v[112:115]
	v_mfma_f32_16x16x32_bf16 v[108:111], v[144:147], v[168:171], v[108:111]
	v_mfma_f32_16x16x32_bf16 v[96:99], v[136:139], v[176:179], v[96:99]
	v_mfma_f32_16x16x32_bf16 v[92:95], v[144:147], v[176:179], v[92:95]
	v_mfma_f32_16x16x32_bf16 v[76:79], v[136:139], v[184:187], v[76:79]
	v_mfma_f32_16x16x32_bf16 v[72:75], v[144:147], v[184:187], v[72:75]
	v_add_u32_e32 v80, 0x1c000, v208
	s_barrier
	ds_read_b128 v[188:191], v80
	ds_read_b128 v[204:207], v80 offset:1024
	ds_read_b128 v[214:217], v80 offset:2048
	ds_read_b128 v[218:221], v80 offset:3072
	s_waitcnt vmcnt(0)
	s_barrier
	s_waitcnt lgkmcnt(0)
	s_waitcnt lgkmcnt(0)
	v_mfma_f32_16x16x32_bf16 v[120:123], v[188:191], v[148:151], v[120:123]
	v_mfma_f32_16x16x32_bf16 v[116:119], v[214:217], v[148:151], v[116:119]
	v_mfma_f32_16x16x32_bf16 v[104:107], v[188:191], v[164:167], v[104:107]
	v_mfma_f32_16x16x32_bf16 v[100:103], v[214:217], v[164:167], v[100:103]
	v_mfma_f32_16x16x32_bf16 v[86:89], v[188:191], v[172:175], v[88:91]
	v_mfma_f32_16x16x32_bf16 v[82:85], v[214:217], v[172:175], v[82:85]
	v_mfma_f32_16x16x32_bf16 v[68:71], v[188:191], v[180:183], v[68:71]
	v_mfma_f32_16x16x32_bf16 v[64:67], v[214:217], v[180:183], v[64:67]
	v_mfma_f32_16x16x32_bf16 v[120:123], v[204:207], v[160:163], v[120:123]
	v_mfma_f32_16x16x32_bf16 v[116:119], v[218:221], v[160:163], v[116:119]
	v_mfma_f32_16x16x32_bf16 v[104:107], v[204:207], v[168:171], v[104:107]
	v_mfma_f32_16x16x32_bf16 v[100:103], v[218:221], v[168:171], v[100:103]
	v_mfma_f32_16x16x32_bf16 v[88:91], v[204:207], v[176:179], v[86:89]
	v_mfma_f32_16x16x32_bf16 v[84:87], v[218:221], v[176:179], v[82:85]
	v_mfma_f32_16x16x32_bf16 v[68:71], v[204:207], v[184:187], v[68:71]
	v_mfma_f32_16x16x32_bf16 v[64:67], v[218:221], v[184:187], v[64:67]
	s_barrier
	ds_read_b128 v[148:151], v209 offset:49152
	ds_read_b128 v[160:163], v209 offset:50176
	ds_read_b128 v[164:167], v209 offset:51200
	ds_read_b128 v[168:171], v209 offset:52224
	ds_read_b128 v[172:175], v209 offset:53248
	ds_read_b128 v[176:179], v209 offset:54272
	ds_read_b128 v[180:183], v209 offset:55296
	ds_read_b128 v[184:187], v209 offset:56320
	s_barrier
	s_waitcnt lgkmcnt(0)
	s_waitcnt lgkmcnt(0)
	v_mfma_f32_16x16x32_bf16 v[60:63], v[132:135], v[148:151], v[60:63]
	v_mfma_f32_16x16x32_bf16 v[56:59], v[140:143], v[148:151], v[56:59]
	v_mfma_f32_16x16x32_bf16 v[44:47], v[132:135], v[164:167], v[44:47]
	v_mfma_f32_16x16x32_bf16 v[40:43], v[140:143], v[164:167], v[40:43]
	v_mfma_f32_16x16x32_bf16 v[28:31], v[132:135], v[172:175], v[28:31]
	v_mfma_f32_16x16x32_bf16 v[24:27], v[140:143], v[172:175], v[24:27]
	v_mfma_f32_16x16x32_bf16 v[12:15], v[132:135], v[180:183], v[12:15]
	v_mfma_f32_16x16x32_bf16 v[8:11], v[140:143], v[180:183], v[8:11]
	v_mfma_f32_16x16x32_bf16 v[60:63], v[136:139], v[160:163], v[60:63]
	v_mfma_f32_16x16x32_bf16 v[56:59], v[144:147], v[160:163], v[56:59]
	v_mfma_f32_16x16x32_bf16 v[44:47], v[136:139], v[168:171], v[44:47]
	v_mfma_f32_16x16x32_bf16 v[40:43], v[144:147], v[168:171], v[40:43]
	v_mfma_f32_16x16x32_bf16 v[28:31], v[136:139], v[176:179], v[28:31]
	v_mfma_f32_16x16x32_bf16 v[24:27], v[144:147], v[176:179], v[24:27]
	v_mfma_f32_16x16x32_bf16 v[12:15], v[136:139], v[184:187], v[12:15]
	v_mfma_f32_16x16x32_bf16 v[8:11], v[144:147], v[184:187], v[8:11]
	v_mfma_f32_16x16x32_bf16 v[52:55], v[188:191], v[148:151], v[52:55]
	v_mfma_f32_16x16x32_bf16 v[48:51], v[214:217], v[148:151], v[48:51]
	v_mfma_f32_16x16x32_bf16 v[36:39], v[188:191], v[164:167], v[36:39]
	v_mfma_f32_16x16x32_bf16 v[32:35], v[214:217], v[164:167], v[32:35]
	v_mfma_f32_16x16x32_bf16 v[20:23], v[188:191], v[172:175], v[20:23]
	v_mfma_f32_16x16x32_bf16 v[16:19], v[214:217], v[172:175], v[16:19]
	v_mfma_f32_16x16x32_bf16 v[4:7], v[188:191], v[180:183], v[4:7]
	v_mfma_f32_16x16x32_bf16 v[0:3], v[214:217], v[180:183], v[0:3]
	v_mfma_f32_16x16x32_bf16 v[52:55], v[204:207], v[160:163], v[52:55]
	v_mfma_f32_16x16x32_bf16 v[48:51], v[218:221], v[160:163], v[48:51]
	v_mfma_f32_16x16x32_bf16 v[36:39], v[204:207], v[168:171], v[36:39]
	v_mfma_f32_16x16x32_bf16 v[32:35], v[218:221], v[168:171], v[32:35]
	v_mfma_f32_16x16x32_bf16 v[20:23], v[204:207], v[176:179], v[20:23]
	v_mfma_f32_16x16x32_bf16 v[16:19], v[218:221], v[176:179], v[16:19]
	v_mfma_f32_16x16x32_bf16 v[4:7], v[204:207], v[184:187], v[4:7]
	v_mfma_f32_16x16x32_bf16 v[0:3], v[218:221], v[184:187], v[0:3]
	s_cmpk_lt_u32 s33, 0x100
	s_barrier
	s_cbranch_scc0 .LBB0_866
	s_barrier
	s_and_b64 s[36:37], s[10:11], s[48:49]
	s_xor_b64 s[42:43], s[36:37], -1
	s_and_b64 vcc, exec, s[42:43]
	s_cbranch_vccnz .LBB0_856
	s_branch .LBB0_867
